# c10 plus v_cvt_pk_bf16_f32 instead of the 5-instruction RNE bit trick in the gating LayerNorm block (bit-identical rounding)
# speedup vs baseline: 1.0028x; 1.0028x over previous
; #define GAS __attribute__((address_space(1)))
; __device__ __forceinline__ float bf2f(unsigned short h) { return __uint_as_float(((unsigned)h) << 16); }
; __device__ __forceinline__ void ph_misc(const Args& a, char* lds, int l) {
;     ...
;         for (int i = 0; i < 16; i += 2) { const int s0 = wave * 16 + i, s1 = s0 + 1;
;             const bf16x8 va = *(const GAS bf16x8*)(P + (row0 + s0) * NIN + PC_V + lane * 8), vb = *(const GAS bf16x8*)(P + (row0 + s1) * NIN + PC_V + lane * 8);
;             float za[8], zb[8]; float suma = 0.f, sqa = 0.f, sumb = 0.f, sqb = 0.f;
; #pragma unroll
;             for (int k = 0; k < 8; ++k) { za[k] = gelu_tanh(bf2f((unsigned short)va[k])); zb[k] = gelu_tanh(bf2f((unsigned short)vb[k])); suma += za[k]; sqa += za[k] * za[k]; sumb += zb[k]; sqb += zb[k] * zb[k]; }
; #pragma unroll
;             for (int o = 1; o < 64; o <<= 1) { const float t0 = __shfl_xor(suma, o), t1 = __shfl_xor(sqa, o), t2 = __shfl_xor(sumb, o), t3 = __shfl_xor(sqb, o); suma += t0; sqa += t1; sumb += t2; sqb += t3; }
.LBB0_662:
	s_mov_b64 s[0:1], 0x4c00
	v_lshl_add_u64 v[208:209], v[26:27], 0, s[0:1]
	v_add_co_u32_e32 v210, vcc, 0x2000, v208
	s_nop 1
	v_addc_co_u32_e32 v211, vcc, 0, v209, vcc
	s_waitcnt vmcnt(0)
	v_mov_b64_e32 v[18:19], v[200:201]
	v_mov_b64_e32 v[20:21], v[202:203]
	v_mov_b64_e32 v[22:23], v[204:205]
	v_mov_b64_e32 v[24:25], v[206:207]
	global_load_dwordx4 v[200:203], v[208:209], off
	global_load_dwordx4 v[204:207], v[210:211], off offset:1536
	v_lshlrev_b32_e32 v90, 16, v18
	v_and_b32_e32 v92, 0xffff0000, v18
	v_lshlrev_b32_e32 v18, 16, v19
	s_waitcnt lgkmcnt(1)
	v_and_b32_e32 v86, 0xffff0000, v19
	v_lshlrev_b32_e32 v88, 16, v20
	v_mul_f32_e32 v19, 0x3d372713, v90
	v_mul_f32_e32 v63, 0x3d372713, v92
	v_mov_b32_e32 v61, v90
	v_mov_b32_e32 v65, v92
	v_mul_f32_e32 v67, 0x3d372713, v18
	v_mul_f32_e32 v82, 0x3d372713, v86
	v_mul_f32_e32 v84, 0x3d372713, v88
	v_lshlrev_b32_e32 v91, 16, v22
	v_mul_f32_e32 v94, v19, v90
	v_and_b32_e32 v93, 0xffff0000, v22
	v_mul_f32_e32 v22, v63, v92
	v_mov_b32_e32 v69, v18
	v_mov_b32_e32 v83, v86
	v_mov_b32_e32 v85, v88
	v_lshlrev_b32_e32 v19, 16, v23
	v_mul_f32_e32 v63, v67, v18
	s_waitcnt lgkmcnt(0)
	v_and_b32_e32 v87, 0xffff0000, v23
	v_mul_f32_e32 v23, v82, v86
	v_mul_f32_e32 v67, v84, v88
	v_fmac_f32_e32 v61, v94, v61
	v_mul_f32_e32 v82, 0x3d372713, v91
	v_fmac_f32_e32 v65, v22, v65
	v_mul_f32_e32 v22, 0x3d372713, v93
	v_mov_b32_e32 v84, v91
	v_mov_b32_e32 v94, v93
	v_fmac_f32_e32 v69, v63, v69
	v_mul_f32_e32 v63, 0x3d372713, v19
	v_fmac_f32_e32 v83, v23, v83
	v_mul_f32_e32 v23, 0x3d372713, v87
	v_fmac_f32_e32 v85, v67, v85
	v_mul_f32_e32 v61, 0x3f4c422a, v61
	v_mul_f32_e32 v67, v82, v91
	v_mul_f32_e32 v65, 0x3f4c422a, v65
	v_mul_f32_e32 v22, v22, v93
	v_mov_b32_e32 v95, v19
	v_mov_b32_e32 v96, v87
	v_mul_f32_e32 v63, v63, v19
	v_mul_f32_e32 v23, v23, v87
	v_mul_f32_e32 v61, 0xc038aa3b, v61
	v_fmac_f32_e32 v84, v67, v84
	v_mul_f32_e32 v65, 0xc038aa3b, v65
	v_fmac_f32_e32 v94, v22, v94
	v_mul_f32_e32 v69, 0x3f4c422a, v69
	v_mul_f32_e32 v82, 0x3f4c422a, v83
	v_fmac_f32_e32 v95, v63, v95
	v_fmac_f32_e32 v96, v23, v96
	v_exp_f32_e32 v23, v61
	v_mul_f32_e32 v61, 0x3f4c422a, v84
	v_exp_f32_e32 v65, v65
	v_mul_f32_e32 v67, 0x3f4c422a, v94
	v_mul_f32_e32 v22, 0xc038aa3b, v69
	v_mul_f32_e32 v63, 0xc038aa3b, v82
	v_mul_f32_e32 v69, 0x3f4c422a, v95
	v_mul_f32_e32 v61, 0xc038aa3b, v61
	v_mul_f32_e32 v67, 0xc038aa3b, v67
	v_exp_f32_e32 v22, v22
	v_exp_f32_e32 v63, v63
	v_mul_f32_e32 v69, 0xc038aa3b, v69
	v_exp_f32_e32 v61, v61
	v_exp_f32_e32 v67, v67
	v_exp_f32_e32 v69, v69
	v_lshlrev_b32_e32 v89, 16, v24
	v_add_f32_e32 v65, 1.0, v65
	v_add_f32_e32 v23, 1.0, v23
	v_rcp_f32_e32 v94, v65
	v_mul_f32_e32 v65, 0x3d372713, v89
	v_mul_f32_e32 v82, 0x3f4c422a, v96
	v_add_f32_e32 v83, 1.0, v22
	v_add_f32_e32 v63, 1.0, v63
	v_rcp_f32_e32 v22, v23
	v_add_f32_e32 v23, 1.0, v61
	v_add_f32_e32 v61, 1.0, v67
	v_mul_f32_e32 v65, v65, v89
	v_mov_b32_e32 v67, v89
	v_mul_f32_e32 v99, 0x3f4c422a, v85
	v_mul_f32_e32 v82, 0xc038aa3b, v82
	v_rcp_f32_e32 v98, v63
	v_add_f32_e32 v63, 1.0, v69
	v_fmac_f32_e32 v67, v65, v67
	v_exp_f32_e32 v82, v82
	v_rcp_f32_e32 v95, v61
	v_rcp_f32_e32 v97, v63
	v_mul_f32_e32 v63, 0xc038aa3b, v99
	v_mul_f32_e32 v65, 0x3f4c422a, v67
	v_rcp_f32_e32 v23, v23
	v_exp_f32_e32 v63, v63
	v_mul_f32_e32 v65, 0xc038aa3b, v65
	v_exp_f32_e32 v65, v65
	v_and_b32_e32 v104, 0xffff0000, v20
	v_mul_f32_e32 v20, 0x3d372713, v104
	v_rcp_f32_e32 v96, v83
	v_add_f32_e32 v61, 1.0, v82
	v_pk_mul_f32 v[82:83], v[94:95], v[92:93]
	v_and_b32_e32 v105, 0xffff0000, v24
	v_mul_f32_e32 v20, v20, v104
	v_mov_b32_e32 v24, v104
	v_pk_mul_f32 v[84:85], v[22:23], v[90:91]
	v_pk_fma_f32 v[90:91], v[22:23], v[90:91], 0 op_sel_hi:[1,1,0]
	v_pk_mul_f32 v[100:101], v[82:83], v[82:83]
	v_rcp_f32_e32 v99, v61
	v_add_f32_e32 v61, 1.0, v63
	v_fmac_f32_e32 v24, v20, v24
	v_pk_fma_f32 v[102:103], v[94:95], v[92:93], v[90:91]
	v_pk_fma_f32 v[90:91], v[84:85], v[84:85], v[100:101]
	v_rcp_f32_e32 v100, v61
	v_add_f32_e32 v61, 1.0, v65
	v_mul_f32_e32 v20, 0x3f4c422a, v24
	v_mul_f32_e32 v24, 0x3d372713, v105
	v_rcp_f32_e32 v101, v61
	v_mul_f32_e32 v24, v24, v105
	v_mov_b32_e32 v61, v105
	v_fmac_f32_e32 v61, v24, v61
	v_mul_f32_e32 v20, 0xc038aa3b, v20
	v_mul_f32_e32 v24, 0x3f4c422a, v61
	v_exp_f32_e32 v20, v20
	v_mul_f32_e32 v24, 0xc038aa3b, v24
	v_exp_f32_e32 v24, v24
	v_lshlrev_b32_e32 v110, 16, v21
	v_add_f32_e32 v20, 1.0, v20
	v_rcp_f32_e32 v108, v20
	v_add_f32_e32 v20, 1.0, v24
	v_rcp_f32_e32 v109, v20
	v_mul_f32_e32 v20, 0x3d372713, v110
	v_mul_f32_e32 v20, v20, v110
	v_mov_b32_e32 v24, v110
	v_lshlrev_b32_e32 v111, 16, v25
	v_fmac_f32_e32 v24, v20, v24
	v_mul_f32_e32 v20, 0x3f4c422a, v24
	v_mul_f32_e32 v24, 0x3d372713, v111
	v_mul_f32_e32 v24, v24, v111
	v_mov_b32_e32 v61, v111
	v_fmac_f32_e32 v61, v24, v61
	v_mul_f32_e32 v20, 0xc038aa3b, v20
	v_mul_f32_e32 v24, 0x3f4c422a, v61
	v_exp_f32_e32 v20, v20
	v_mul_f32_e32 v24, 0xc038aa3b, v24
	v_exp_f32_e32 v24, v24
	v_and_b32_e32 v114, 0xffff0000, v21
	v_add_f32_e32 v20, 1.0, v20
	v_mul_f32_e32 v21, 0x3d372713, v114
	v_rcp_f32_e32 v112, v20
	v_add_f32_e32 v20, 1.0, v24
	v_mul_f32_e32 v21, v21, v114
	v_mov_b32_e32 v24, v114
	v_and_b32_e32 v115, 0xffff0000, v25
	v_fmac_f32_e32 v24, v21, v24
	v_mul_f32_e32 v21, 0x3f4c422a, v24
	v_mul_f32_e32 v24, 0x3d372713, v115
	v_mul_f32_e32 v24, v24, v115
	v_mov_b32_e32 v25, v115
	v_fmac_f32_e32 v25, v24, v25
	v_mul_f32_e32 v21, 0xc038aa3b, v21
	v_mul_f32_e32 v24, 0x3f4c422a, v25
	v_exp_f32_e32 v21, v21
	v_mul_f32_e32 v24, 0xc038aa3b, v24
	v_exp_f32_e32 v24, v24
	v_rcp_f32_e32 v113, v20
	v_add_f32_e32 v20, 1.0, v21
	v_pk_mul_f32 v[22:23], v[96:97], v[18:19]
	v_rcp_f32_e32 v116, v20
	v_add_f32_e32 v20, 1.0, v24
	v_pk_fma_f32 v[90:91], v[22:23], v[22:23], v[90:91]
	v_pk_mul_f32 v[92:93], v[98:99], v[86:87]
	v_rcp_f32_e32 v117, v20
	v_pk_fma_f32 v[18:19], v[96:97], v[18:19], v[102:103]
	v_pk_fma_f32 v[94:95], v[92:93], v[92:93], v[90:91]
	v_pk_mul_f32 v[90:91], v[100:101], v[88:89]
	v_pk_fma_f32 v[18:19], v[98:99], v[86:87], v[18:19]
	v_pk_fma_f32 v[106:107], v[90:91], v[90:91], v[94:95]
	v_pk_mul_f32 v[94:95], v[108:109], v[104:105]
	v_pk_fma_f32 v[18:19], v[100:101], v[88:89], v[18:19]
	v_pk_fma_f32 v[20:21], v[94:95], v[94:95], v[106:107]
	v_pk_mul_f32 v[24:25], v[112:113], v[110:111]
	v_pk_fma_f32 v[18:19], v[108:109], v[104:105], v[18:19]
	v_pk_fma_f32 v[106:107], v[24:25], v[24:25], v[20:21]
	v_pk_mul_f32 v[20:21], v[116:117], v[114:115]
	v_pk_fma_f32 v[18:19], v[112:113], v[110:111], v[18:19]
	v_pk_fma_f32 v[106:107], v[20:21], v[20:21], v[106:107]
	v_pk_fma_f32 v[18:19], v[116:117], v[114:115], v[18:19]
	ds_bpermute_b32 v61, v43, v106
	ds_bpermute_b32 v63, v43, v107
	ds_bpermute_b32 v86, v43, v18
	ds_bpermute_b32 v87, v43, v19
	s_waitcnt lgkmcnt(3)
; #define LAS __attribute__((address_space(3)))
; __device__ __forceinline__ unsigned f2bf(float f) { unsigned u = __float_as_uint(f); return (u + 0x7fffu + ((u >> 16) & 1u)) >> 16; }
; __device__ __forceinline__ void ph_misc(const Args& a, char* lds, int l) {
;     ...
;             for (int o = 1; o < 64; o <<= 1) { const float t0 = __shfl_xor(suma, o), t1 = __shfl_xor(sqa, o), t2 = __shfl_xor(sumb, o), t3 = __shfl_xor(sqb, o); suma += t0; sqa += t1; sumb += t2; sqb += t3; }
;             const float meana = suma * (1.0f / 512.0f), meanb = sumb * (1.0f / 512.0f);
;             const float rstda = 1.0f / sqrtf(fmaxf(sqa * (1.0f / 512.0f) - meana * meana, 0.f) + EPSN), rstdb = 1.0f / sqrtf(fmaxf(sqb * (1.0f / 512.0f) - meanb * meanb, 0.f) + EPSN);
;             if (mine) {
; #pragma unroll
;                 for (int k = 0; k < 8; ++k) { *(LAS bf16_t*)(Vt + (cl + k) * 272 + s0 * 2) = (bf16_t)f2bf((za[k] - meana) * rstda * gg[k] + bb[k]);
;                                               *(LAS bf16_t*)(Vt + (cl + k) * 272 + s1 * 2) = (bf16_t)f2bf((zb[k] - meanb) * rstdb * gg[k] + bb[k]); } } }
	v_add_f32_e32 v61, v106, v61
	s_waitcnt lgkmcnt(2)
	v_add_f32_e32 v63, v107, v63
	ds_bpermute_b32 v65, v45, v61
	s_waitcnt lgkmcnt(1)
	v_pk_add_f32 v[18:19], v[18:19], v[86:87]
	ds_bpermute_b32 v67, v45, v63
	ds_bpermute_b32 v86, v45, v18
	ds_bpermute_b32 v87, v45, v19
	s_waitcnt lgkmcnt(3)
	v_add_f32_e32 v61, v61, v65
	ds_bpermute_b32 v65, v47, v61
	s_waitcnt lgkmcnt(3)
	v_add_f32_e32 v63, v63, v67
	ds_bpermute_b32 v67, v47, v63
	s_waitcnt lgkmcnt(2)
	v_pk_add_f32 v[18:19], v[18:19], v[86:87]
	ds_bpermute_b32 v86, v47, v18
	ds_bpermute_b32 v87, v47, v19
	s_waitcnt lgkmcnt(3)
	v_add_f32_e32 v61, v61, v65
	s_waitcnt lgkmcnt(2)
	v_add_f32_e32 v63, v63, v67
	ds_bpermute_b32 v65, v49, v61
	ds_bpermute_b32 v67, v49, v63
	s_waitcnt lgkmcnt(2)
	v_pk_add_f32 v[18:19], v[18:19], v[86:87]
	ds_bpermute_b32 v86, v49, v18
	ds_bpermute_b32 v87, v49, v19
	s_waitcnt lgkmcnt(3)
	v_add_f32_e32 v61, v61, v65
	s_waitcnt lgkmcnt(2)
	v_add_f32_e32 v63, v63, v67
	ds_bpermute_b32 v65, v51, v61
	ds_bpermute_b32 v67, v51, v63
	s_waitcnt lgkmcnt(2)
	v_pk_add_f32 v[18:19], v[18:19], v[86:87]
	ds_bpermute_b32 v86, v51, v18
	ds_bpermute_b32 v87, v51, v19
	s_waitcnt lgkmcnt(3)
	v_add_f32_e32 v61, v61, v65
	s_waitcnt lgkmcnt(2)
	v_add_f32_e32 v65, v63, v67
	ds_bpermute_b32 v63, v53, v61
	ds_bpermute_b32 v67, v53, v65
	s_waitcnt lgkmcnt(2)
	v_pk_add_f32 v[18:19], v[18:19], v[86:87]
	ds_bpermute_b32 v86, v53, v18
	ds_bpermute_b32 v87, v53, v19
	s_and_saveexec_b64 s[0:1], s[6:7]
	s_cbranch_execz .LBB0_661
	s_waitcnt lgkmcnt(0)
	v_pk_add_f32 v[18:19], v[18:19], v[86:87]
	v_add_f32_e32 v88, v65, v67
	v_pk_mul_f32 v[86:87], v[18:19], s[42:43] op_sel_hi:[1,0]
	s_mov_b32 s40, 0xf800000
	v_mov_b32_e32 v89, v87
	v_mov_b32_e32 v195, v87
	v_pk_mul_f32 v[88:89], v[88:89], v[194:195]
	v_mov_b32_e32 v195, v86
	v_sub_f32_e32 v65, v88, v89
	v_max_f32_e32 v65, 0, v65
	v_add_f32_e32 v65, 0x358637bd, v65
	v_mul_f32_e32 v67, 0x4f800000, v65
	v_cmp_gt_f32_e32 vcc, s40, v65
	v_add_f32_e32 v88, v61, v63
	v_mov_b32_e32 v89, v86
	v_cndmask_b32_e32 v65, v65, v67, vcc
	v_sqrt_f32_e32 v67, v65
	v_pk_mul_f32 v[86:87], v[88:89], v[194:195]
	v_pk_fma_f32 v[84:85], v[18:19], s[42:43], v[84:85] op_sel_hi:[1,0,1] neg_lo:[1,0,0] neg_hi:[1,0,0]
	v_pk_fma_f32 v[82:83], v[18:19], s[42:43], v[82:83] op_sel_hi:[1,0,1] neg_lo:[1,0,0] neg_hi:[1,0,0]
	v_add_u32_e32 v61, -1, v67
	v_fma_f32 v63, -v61, v67, v65
	v_cmp_ge_f32_e64 s[8:9], 0, v63
	v_add_u32_e32 v63, 1, v67
	v_pk_fma_f32 v[22:23], v[18:19], s[42:43], v[22:23] op_sel_hi:[1,0,1] neg_lo:[1,0,0] neg_hi:[1,0,0]
	v_cndmask_b32_e64 v61, v67, v61, s[8:9]
	v_fma_f32 v67, -v63, v67, v65
	v_cmp_lt_f32_e64 s[8:9], 0, v67
	v_sub_f32_e32 v67, v86, v87
	v_max_f32_e32 v67, 0, v67
	v_add_f32_e32 v67, 0x358637bd, v67
	v_cndmask_b32_e64 v61, v61, v63, s[8:9]
	v_mul_f32_e32 v69, 0x4f800000, v67
	v_cmp_gt_f32_e64 s[8:9], s40, v67
	v_mul_f32_e32 v63, 0x37800000, v61
	v_cndmask_b32_e32 v61, v61, v63, vcc
	v_cndmask_b32_e64 v67, v67, v69, s[8:9]
	v_sqrt_f32_e32 v69, v67
	v_cmp_class_f32_e32 vcc, v65, v247
	v_add_u32_e32 v63, -1, v69
	s_nop 0
	v_cndmask_b32_e32 v61, v61, v65, vcc
	v_fma_f32 v65, -v63, v69, v67
	v_cmp_ge_f32_e32 vcc, 0, v65
	v_add_u32_e32 v65, 1, v69
	s_nop 0
	v_cndmask_b32_e32 v63, v69, v63, vcc
	v_fma_f32 v69, -v65, v69, v67
	v_cmp_lt_f32_e32 vcc, 0, v69
	v_div_scale_f32 v69, s[40:41], v61, v61, 1.0
	v_rcp_f32_e32 v86, v69
	v_cndmask_b32_e32 v63, v63, v65, vcc
	v_mul_f32_e32 v65, 0x37800000, v63
	v_cndmask_b32_e64 v63, v63, v65, s[8:9]
	v_cmp_class_f32_e32 vcc, v67, v247
	v_fma_f32 v65, -v69, v86, 1.0
	v_fmac_f32_e32 v86, v65, v86
	v_cndmask_b32_e32 v63, v63, v67, vcc
	v_div_scale_f32 v65, vcc, 1.0, v61, 1.0
	v_mul_f32_e32 v67, v65, v86
	v_fma_f32 v87, -v69, v67, v65
	v_fmac_f32_e32 v67, v87, v86
	v_fma_f32 v65, -v69, v67, v65
	v_div_scale_f32 v69, s[8:9], v63, v63, 1.0
	v_rcp_f32_e32 v88, v69
	v_div_fmas_f32 v65, v65, v86, v67
	v_div_fixup_f32 v87, v65, v61, 1.0
	v_fma_f32 v61, -v69, v88, 1.0
	v_fmac_f32_e32 v88, v61, v88
	v_div_scale_f32 v61, vcc, 1.0, v63, 1.0
	v_mul_f32_e32 v65, v61, v88
	v_fma_f32 v67, -v69, v65, v61
	v_fmac_f32_e32 v65, v67, v88
	v_fma_f32 v61, -v69, v65, v61
	v_div_fmas_f32 v61, v61, v88, v65
	v_div_fixup_f32 v86, v61, v63, 1.0
	v_pk_mul_f32 v[84:85], v[84:85], v[86:87]
	v_pk_mul_f32 v[82:83], v[82:83], v[86:87]
	v_pk_fma_f32 v[84:85], v[30:31], v[84:85], v[28:29]
	v_pk_fma_f32 v[82:83], v[6:7], v[82:83], v[2:3]
	v_cvt_pk_bf16_f32 v61, v84, v85
	v_pk_mul_f32 v[22:23], v[22:23], v[86:87]
	v_cvt_pk_bf16_f32 v63, v82, v83
	v_pk_fma_f32 v[22:23], v[72:73], v[22:23], v[32:33]
	ds_write2_b32 v0, v61, v63 offset1:68
	v_cvt_pk_bf16_f32 v61, v22, v23
	v_pk_fma_f32 v[22:23], v[18:19], s[42:43], v[92:93] op_sel_hi:[1,0,1] neg_lo:[1,0,0] neg_hi:[1,0,0]
	s_nop 0
	v_pk_mul_f32 v[22:23], v[22:23], v[86:87]
	s_nop 0
	v_pk_fma_f32 v[22:23], v[8:9], v[22:23], v[4:5]
	s_nop 0
	v_cvt_pk_bf16_f32 v22, v22, v23
	ds_write2_b32 v0, v61, v22 offset0:136 offset1:204
	v_pk_fma_f32 v[22:23], v[18:19], s[42:43], v[90:91] op_sel_hi:[1,0,1] neg_lo:[1,0,0] neg_hi:[1,0,0]
	s_nop 0
	v_pk_mul_f32 v[22:23], v[22:23], v[86:87]
	s_nop 0
	v_pk_fma_f32 v[22:23], v[76:77], v[22:23], v[74:75]
	s_nop 0
	v_cvt_pk_bf16_f32 v61, v22, v23
	v_pk_fma_f32 v[22:23], v[18:19], s[42:43], v[94:95] op_sel_hi:[1,0,1] neg_lo:[1,0,0] neg_hi:[1,0,0]
	s_nop 0
	v_pk_mul_f32 v[22:23], v[22:23], v[86:87]
	s_nop 0
	v_pk_fma_f32 v[22:23], v[14:15], v[22:23], v[10:11]
	s_nop 0
	v_cvt_pk_bf16_f32 v22, v22, v23
	v_add_u32_e32 v63, 0x400, v0
	ds_write2_b32 v63, v61, v22 offset0:16 offset1:84
	v_pk_fma_f32 v[22:23], v[18:19], s[42:43], v[24:25] op_sel_hi:[1,0,1] neg_lo:[1,0,0] neg_hi:[1,0,0]
	v_pk_fma_f32 v[18:19], v[18:19], s[42:43], v[20:21] op_sel_hi:[1,0,1] neg_lo:[1,0,0] neg_hi:[1,0,0]
	v_pk_mul_f32 v[22:23], v[22:23], v[86:87]
	v_pk_mul_f32 v[18:19], v[18:19], v[86:87]
	v_pk_fma_f32 v[22:23], v[80:81], v[22:23], v[78:79]
	v_pk_fma_f32 v[18:19], v[16:17], v[18:19], v[12:13]
	v_cvt_pk_bf16_f32 v22, v22, v23
	v_cvt_pk_bf16_f32 v18, v18, v19
	ds_write2_b32 v63, v22, v18 offset0:152 offset1:220
	s_branch .LBB0_661
